# layer-1 in-proj weight transpose/convert moved from the serial prologue phase into layer 0's phase 3, run by the 224 workgroups that have no compress-GEMM tile there (the buffer is free after layer 0'
# speedup vs baseline: 1.0085x; 1.0085x over previous
; __device__ __forceinline__ float bfhi(unsigned w) { return __uint_as_float(w & 0xffff0000u); }
; __device__ __forceinline__ void prologue(LAS unsigned char* lds, const Ctx& P, int l) {
;     ...
;     for (int t = blockIdx.x; t < T_ALL; t += G) {
;         int q = t;
;         if (q < T_IN) { const int kt = q & 31, ntl = q >> 5; tconv_tile(tile, P.in[3] + (size_t)l * DM * INW, INW, kt * 64, ntl * 64, 1, (bf16_t*)(ws + WS_WIN), DM); continue; }
; __global__ void __launch_bounds__(512, 2) fwd_megakernel(Params PK) {
;     ...
;         } else if (ph == 3) {
;             { const unsigned* LRW = (const unsigned*)(ws + WS_LRA); float* AGP = (float*)(ws + WS_AGG); float* AGH = AGP + 128 * 1024;
;                 for (size_t id = gtid; id < (size_t)128 * 1024; id += gstride) { const int ch = (int)(id & 1023), bc = (int)(id >> 10); const size_t base = (size_t)bc * 128 * DBR + ch;
;                     float p = 1.f, h = 0.f; const float sc = fmaxf(1.0f - __expf(-((const float*)(ws + WS_PEW1))[512 + ch]), 1e-30f) * (1.0f / 65535.0f);
; #pragma unroll 8
;                     for (int t = 0; t < 128; ++t) { const unsigned w = LRW[base + (size_t)t * DBR]; const float a = 1.0f - (float)(w & 0xffffu) * sc, g = bfhi(w); p *= a; h = a * h + g; }
;                     AGP[id] = p; AGH[id] = h; } }
;             { pg8::SchedCmp1 S{bid, (const bf16_t*)(ws + WS_A0), (const bf16_t*)(ws + WS_W1T)}; pg8::EpiBf16 E{(bf16_t*)(ws + WS_HID), 256, (size_t)4096 * 256, (const float*)(ws + WS_PEW1), 256, 2}; pg8::gemm_phase(lds, 2048, S, E); }
.Lp3_tc:
	s_cmp_lg_u32 s70, 3
	s_cbranch_scc1 .LBB0_786
	s_cmp_lt_u32 s2, 32
	s_cbranch_scc1 .LBB0_786
.Lp3_tc_go:
	v_mov_b32_e32 v26, 0x23f00
	ds_read_b64 v[34:35], v26 offset:24
	ds_read_b64 v[36:37], v26 offset:184
	ds_read_b64 v[38:39], v26 offset:192
	ds_read_b64 v[40:41], v26 offset:176
	ds_read_b64 v[42:43], v26 offset:136
	ds_read_b64 v[44:45], v26 offset:144
	ds_read_b64 v[46:47], v26 offset:80
	ds_read_b64 v[48:49], v26 offset:96
	s_waitcnt lgkmcnt(0)
	v_readfirstlane_b32 s4, v34
	v_readfirstlane_b32 s5, v35
	v_readfirstlane_b32 s6, v36
	v_readfirstlane_b32 s7, v37
	v_readfirstlane_b32 s8, v38
	v_readfirstlane_b32 s9, v39
	v_readfirstlane_b32 s10, v40
	v_readfirstlane_b32 s11, v41
	v_readfirstlane_b32 s12, v42
	v_readfirstlane_b32 s13, v43
	v_readfirstlane_b32 s14, v44
	v_readfirstlane_b32 s15, v45
	v_readfirstlane_b32 s16, v46
	v_readfirstlane_b32 s17, v47
	v_readfirstlane_b32 s18, v48
	v_readfirstlane_b32 s19, v49
	s_nop 3
	s_add_u32 s4, s4, 0x9460000
	s_addc_u32 s5, s5, 0
	s_add_u32 s6, s6, 0x2000000
	s_addc_u32 s7, s7, 0
	s_add_u32 s8, s8, 0x1000000
	s_addc_u32 s9, s9, 0
	s_add_u32 s10, s10, 0x1000000
	s_addc_u32 s11, s11, 0
	s_add_u32 s12, s12, 0x200000
	s_addc_u32 s13, s13, 0
	s_add_u32 s14, s14, 0x200000
	s_addc_u32 s15, s15, 0
	s_add_u32 s16, s16, 0x80000
	s_addc_u32 s17, s17, 0
	s_add_u32 s18, s18, 0x80000
	s_addc_u32 s19, s19, 0
	v_lshrrev_b32_e32 v20, 4, v234
	v_and_b32_e32 v21, 15, v234
	v_lshlrev_b32_e32 v21, 2, v21
	v_mul_u32_u24_e32 v22, 0x104, v20
	v_lshl_add_u32 v22, v21, 2, v22
	v_lshrrev_b32_e32 v24, 3, v234
	v_and_b32_e32 v25, 7, v234
	v_lshlrev_b32_e32 v25, 3, v25
	v_mul_u32_u24_e32 v23, 0x104, v25
	v_lshl_add_u32 v23, v24, 2, v23
	s_sub_u32 s24, s2, 32
	s_mov_b32 s25, s24
	s_min_u32 s0, s24, 9599
	s_mov_b32 s21, s0
	s_mov_b32 s0, s21
	s_cmpk_lt_u32 s0, 9600
	s_cbranch_scc0 .Ltc2_c2
	s_and_b32 s1, s0, 31
	s_lshl_b32 s1, s1, 6
	s_lshr_b32 s21, s0, 5
	s_lshl_b32 s21, s21, 6
	s_movk_i32 s29, 64
	s_cmpk_lt_u32 s21, 7680
	s_cbranch_scc1 .Ltc2_n4
	s_cmpk_lt_u32 s21, 18944
	s_cbranch_scc0 .Ltc2_t3
	s_add_u32 s21, s21, 48
	s_branch .Ltc2_n4

; #define LAS __attribute__((address_space(3)))
; __device__ __forceinline__ int opaque_tid() { int t = threadIdx.x; asm volatile("" : "+v"(t)); return t; }
; __device__ __forceinline__ void tconv_tile(LAS float* tile, const float* src, int ld, int k0, int n0, int mode, bf16_t* dst, int K) {
;     const int tid = opaque_tid();
; #pragma unroll
;     for (int it = 0; it < 2; ++it) { const int idx = tid + it * 512, kk = idx >> 4, n4 = (idx & 15) * 4, nn = n0 + n4; int oc = nn; bool valid = true;
;         if (mode == 1) { if (nn < 7680) oc = nn; else if (nn < 18944) oc = nn + 48; else if (nn < INW) oc = 7680 + (nn - 18944); else valid = false; }
;         f32x4 v = (f32x4){0.f, 0.f, 0.f, 0.f}; if (valid) v = *(const f32x4*)(src + (size_t)(k0 + kk) * ld + oc);
;         tile[kk * 65 + n4 + 0] = v[0]; tile[kk * 65 + n4 + 1] = v[1]; tile[kk * 65 + n4 + 2] = v[2]; tile[kk * 65 + n4 + 3] = v[3]; }
; __device__ __forceinline__ void prologue(LAS unsigned char* lds, const Ctx& P, int l) {
;     ...
;         if (q < T_IN) { const int kt = q & 31, ntl = q >> 5; tconv_tile(tile, P.in[3] + (size_t)l * DM * INW, INW, kt * 64, ntl * 64, 1, (bf16_t*)(ws + WS_WIN), DM); continue; }
.Ltc2_d1:
	v_mov_b32_e32 v34, 0
	v_mov_b32_e32 v35, 0
	v_mov_b32_e32 v36, 0
	v_mov_b32_e32 v37, 0
	v_mov_b32_e32 v38, 0
	v_mov_b32_e32 v39, 0
	v_mov_b32_e32 v40, 0
	v_mov_b32_e32 v41, 0
	v_mul_u32_u24_e32 v26, s28, v20
	v_add_lshl_u32 v26, v26, v21, 2
	s_lshl_b32 s0, s28, 7
	v_add_u32_e32 v27, s0, v26
	v_cmp_gt_i32_e32 vcc, s29, v21
	s_and_saveexec_b64 s[0:1], vcc
	global_load_dwordx4 v[34:37], v26, s[26:27]
	global_load_dwordx4 v[38:41], v27, s[26:27]
	s_mov_b64 exec, s[0:1]
	s_add_u32 s24, s24, 0xe0
	s_min_u32 s0, s24, 9599
	s_mov_b32 s21, s0
	s_mov_b32 s0, s21
	s_cmpk_lt_u32 s0, 9600
	s_cbranch_scc0 .Ltc2_c15
	s_and_b32 s1, s0, 31
	s_lshl_b32 s1, s1, 6
	s_lshr_b32 s21, s0, 5
	s_lshl_b32 s21, s21, 6
	s_movk_i32 s29, 64
	s_cmpk_lt_u32 s21, 7680
	s_cbranch_scc1 .Ltc2_n17
	s_cmpk_lt_u32 s21, 18944
	s_cbranch_scc0 .Ltc2_t16
	s_add_u32 s21, s21, 48
	s_branch .Ltc2_n17

; #define LAS __attribute__((address_space(3)))
; __device__ __forceinline__ int opaque_tid() { int t = threadIdx.x; asm volatile("" : "+v"(t)); return t; }
; __device__ __forceinline__ void tconv_tile(LAS float* tile, const float* src, int ld, int k0, int n0, int mode, bf16_t* dst, int K) {
;     const int tid = opaque_tid();
; #pragma unroll
;     for (int it = 0; it < 2; ++it) { const int idx = tid + it * 512, kk = idx >> 4, n4 = (idx & 15) * 4, nn = n0 + n4; int oc = nn; bool valid = true;
;         if (mode == 1) { if (nn < 7680) oc = nn; else if (nn < 18944) oc = nn + 48; else if (nn < INW) oc = 7680 + (nn - 18944); else valid = false; }
;         f32x4 v = (f32x4){0.f, 0.f, 0.f, 0.f}; if (valid) v = *(const f32x4*)(src + (size_t)(k0 + kk) * ld + oc);
;         tile[kk * 65 + n4 + 0] = v[0]; tile[kk * 65 + n4 + 1] = v[1]; tile[kk * 65 + n4 + 2] = v[2]; tile[kk * 65 + n4 + 3] = v[3]; }
; __device__ __forceinline__ void prologue(LAS unsigned char* lds, const Ctx& P, int l) {
;     ...
;         if (q < T_IN) { const int kt = q & 31, ntl = q >> 5; tconv_tile(tile, P.in[3] + (size_t)l * DM * INW, INW, kt * 64, ntl * 64, 1, (bf16_t*)(ws + WS_WIN), DM); continue; }
.Ltc2_d14:
	v_mov_b32_e32 v42, 0
	v_mov_b32_e32 v43, 0
	v_mov_b32_e32 v44, 0
	v_mov_b32_e32 v45, 0
	v_mov_b32_e32 v46, 0
	v_mov_b32_e32 v47, 0
	v_mov_b32_e32 v48, 0
	v_mov_b32_e32 v49, 0
	v_mul_u32_u24_e32 v26, s28, v20
	v_add_lshl_u32 v26, v26, v21, 2
	s_lshl_b32 s0, s28, 7
	v_add_u32_e32 v27, s0, v26
	v_cmp_gt_i32_e32 vcc, s29, v21
	s_and_saveexec_b64 s[0:1], vcc
	global_load_dwordx4 v[42:45], v26, s[26:27]
	global_load_dwordx4 v[46:49], v27, s[26:27]
	s_mov_b64 exec, s[0:1]
	s_add_u32 s24, s24, 0xe0
	s_min_u32 s0, s24, 9599
	s_mov_b32 s21, s0
	s_mov_b32 s0, s21
	s_cmpk_lt_u32 s0, 9600
	s_cbranch_scc0 .Ltc2_c28
	s_and_b32 s1, s0, 31
	s_lshl_b32 s1, s1, 6
	s_lshr_b32 s21, s0, 5
	s_lshl_b32 s21, s21, 6
	s_movk_i32 s29, 64
	s_cmpk_lt_u32 s21, 7680
	s_cbranch_scc1 .Ltc2_n30
	s_cmpk_lt_u32 s21, 18944
	s_cbranch_scc0 .Ltc2_t29
	s_add_u32 s21, s21, 48
	s_branch .Ltc2_n30

; #define LAS __attribute__((address_space(3)))
; __device__ __forceinline__ int opaque_tid() { int t = threadIdx.x; asm volatile("" : "+v"(t)); return t; }
; __device__ __forceinline__ void tconv_tile(LAS float* tile, const float* src, int ld, int k0, int n0, int mode, bf16_t* dst, int K) {
;     const int tid = opaque_tid();
; #pragma unroll
;     for (int it = 0; it < 2; ++it) { const int idx = tid + it * 512, kk = idx >> 4, n4 = (idx & 15) * 4, nn = n0 + n4; int oc = nn; bool valid = true;
;         if (mode == 1) { if (nn < 7680) oc = nn; else if (nn < 18944) oc = nn + 48; else if (nn < INW) oc = 7680 + (nn - 18944); else valid = false; }
;         f32x4 v = (f32x4){0.f, 0.f, 0.f, 0.f}; if (valid) v = *(const f32x4*)(src + (size_t)(k0 + kk) * ld + oc);
;         tile[kk * 65 + n4 + 0] = v[0]; tile[kk * 65 + n4 + 1] = v[1]; tile[kk * 65 + n4 + 2] = v[2]; tile[kk * 65 + n4 + 3] = v[3]; }
; __device__ __forceinline__ void prologue(LAS unsigned char* lds, const Ctx& P, int l) {
;     ...
;         if (q < T_IN) { const int kt = q & 31, ntl = q >> 5; tconv_tile(tile, P.in[3] + (size_t)l * DM * INW, INW, kt * 64, ntl * 64, 1, (bf16_t*)(ws + WS_WIN), DM); continue; }
.Ltc2_d27:
	v_mov_b32_e32 v50, 0
	v_mov_b32_e32 v51, 0
	v_mov_b32_e32 v52, 0
	v_mov_b32_e32 v53, 0
	v_mov_b32_e32 v54, 0
	v_mov_b32_e32 v55, 0
	v_mov_b32_e32 v56, 0
	v_mov_b32_e32 v57, 0
	v_mul_u32_u24_e32 v26, s28, v20
	v_add_lshl_u32 v26, v26, v21, 2
	s_lshl_b32 s0, s28, 7
	v_add_u32_e32 v27, s0, v26
	v_cmp_gt_i32_e32 vcc, s29, v21
	s_and_saveexec_b64 s[0:1], vcc
	global_load_dwordx4 v[50:53], v26, s[26:27]
	global_load_dwordx4 v[54:57], v27, s[26:27]
	s_mov_b64 exec, s[0:1]
	s_add_u32 s24, s24, 0xe0
	s_min_u32 s0, s24, 9599
	s_mov_b32 s21, s0
	s_mov_b32 s0, s21
	s_cmpk_lt_u32 s0, 9600
	s_cbranch_scc0 .Ltc2_c41
	s_and_b32 s1, s0, 31
	s_lshl_b32 s1, s1, 6
	s_lshr_b32 s21, s0, 5
	s_lshl_b32 s21, s21, 6
	s_movk_i32 s29, 64
	s_cmpk_lt_u32 s21, 7680
	s_cbranch_scc1 .Ltc2_n43
	s_cmpk_lt_u32 s21, 18944
	s_cbranch_scc0 .Ltc2_t42
	s_add_u32 s21, s21, 48
	s_branch .Ltc2_n43

; #define LAS __attribute__((address_space(3)))
; __device__ __forceinline__ int opaque_tid() { int t = threadIdx.x; asm volatile("" : "+v"(t)); return t; }
; __device__ __forceinline__ void tconv_tile(LAS float* tile, const float* src, int ld, int k0, int n0, int mode, bf16_t* dst, int K) {
;     const int tid = opaque_tid();
; #pragma unroll
;     for (int it = 0; it < 2; ++it) { const int idx = tid + it * 512, kk = idx >> 4, n4 = (idx & 15) * 4, nn = n0 + n4; int oc = nn; bool valid = true;
;         if (mode == 1) { if (nn < 7680) oc = nn; else if (nn < 18944) oc = nn + 48; else if (nn < INW) oc = 7680 + (nn - 18944); else valid = false; }
;         f32x4 v = (f32x4){0.f, 0.f, 0.f, 0.f}; if (valid) v = *(const f32x4*)(src + (size_t)(k0 + kk) * ld + oc);
;         tile[kk * 65 + n4 + 0] = v[0]; tile[kk * 65 + n4 + 1] = v[1]; tile[kk * 65 + n4 + 2] = v[2]; tile[kk * 65 + n4 + 3] = v[3]; }
; __device__ __forceinline__ void prologue(LAS unsigned char* lds, const Ctx& P, int l) {
;     ...
;         if (q < T_IN) { const int kt = q & 31, ntl = q >> 5; tconv_tile(tile, P.in[3] + (size_t)l * DM * INW, INW, kt * 64, ntl * 64, 1, (bf16_t*)(ws + WS_WIN), DM); continue; }
.Ltc2_d40:
	v_mov_b32_e32 v58, 0
	v_mov_b32_e32 v59, 0
	v_mov_b32_e32 v60, 0
	v_mov_b32_e32 v61, 0
	v_mov_b32_e32 v62, 0
	v_mov_b32_e32 v63, 0
	v_mov_b32_e32 v64, 0
	v_mov_b32_e32 v65, 0
	v_mul_u32_u24_e32 v26, s28, v20
	v_add_lshl_u32 v26, v26, v21, 2
	s_lshl_b32 s0, s28, 7
	v_add_u32_e32 v27, s0, v26
	v_cmp_gt_i32_e32 vcc, s29, v21
	s_and_saveexec_b64 s[0:1], vcc
	global_load_dwordx4 v[58:61], v26, s[26:27]
	global_load_dwordx4 v[62:65], v27, s[26:27]
	s_mov_b64 exec, s[0:1]
	s_add_u32 s24, s24, 0xe0
	s_min_u32 s0, s24, 9599
	s_mov_b32 s21, s0
	s_mov_b32 s0, s21
	s_cmpk_lt_u32 s0, 9600
	s_cbranch_scc0 .Ltc2_c54
	s_and_b32 s1, s0, 31
	s_lshl_b32 s1, s1, 6
	s_lshr_b32 s21, s0, 5
	s_lshl_b32 s21, s21, 6
	s_movk_i32 s29, 64
	s_cmpk_lt_u32 s21, 7680
	s_cbranch_scc1 .Ltc2_n56
	s_cmpk_lt_u32 s21, 18944
	s_cbranch_scc0 .Ltc2_t55
	s_add_u32 s21, s21, 48
	s_branch .Ltc2_n56

; #define LAS __attribute__((address_space(3)))
; __device__ __forceinline__ int opaque_tid() { int t = threadIdx.x; asm volatile("" : "+v"(t)); return t; }
; __device__ __forceinline__ void tconv_tile(LAS float* tile, const float* src, int ld, int k0, int n0, int mode, bf16_t* dst, int K) {
;     const int tid = opaque_tid();
; #pragma unroll
;     for (int it = 0; it < 2; ++it) { const int idx = tid + it * 512, kk = idx >> 4, n4 = (idx & 15) * 4, nn = n0 + n4; int oc = nn; bool valid = true;
;         if (mode == 1) { if (nn < 7680) oc = nn; else if (nn < 18944) oc = nn + 48; else if (nn < INW) oc = 7680 + (nn - 18944); else valid = false; }
;         f32x4 v = (f32x4){0.f, 0.f, 0.f, 0.f}; if (valid) v = *(const f32x4*)(src + (size_t)(k0 + kk) * ld + oc);
;         tile[kk * 65 + n4 + 0] = v[0]; tile[kk * 65 + n4 + 1] = v[1]; tile[kk * 65 + n4 + 2] = v[2]; tile[kk * 65 + n4 + 3] = v[3]; }
; __device__ __forceinline__ void prologue(LAS unsigned char* lds, const Ctx& P, int l) {
;     ...
;         if (q < T_IN) { const int kt = q & 31, ntl = q >> 5; tconv_tile(tile, P.in[3] + (size_t)l * DM * INW, INW, kt * 64, ntl * 64, 1, (bf16_t*)(ws + WS_WIN), DM); continue; }
.Ltc2_d53:
	v_mov_b32_e32 v78, 0
	v_mov_b32_e32 v79, 0
	v_mov_b32_e32 v80, 0
	v_mov_b32_e32 v81, 0
	v_mov_b32_e32 v82, 0
	v_mov_b32_e32 v83, 0
	v_mov_b32_e32 v84, 0
	v_mov_b32_e32 v85, 0
	v_mul_u32_u24_e32 v26, s28, v20
	v_add_lshl_u32 v26, v26, v21, 2
	s_lshl_b32 s0, s28, 7
	v_add_u32_e32 v27, s0, v26
	v_cmp_gt_i32_e32 vcc, s29, v21
	s_and_saveexec_b64 s[0:1], vcc
	global_load_dwordx4 v[78:81], v26, s[26:27]
	global_load_dwordx4 v[82:85], v27, s[26:27]
	s_mov_b64 exec, s[0:1]
	s_add_u32 s24, s24, 0xe0
	s_min_u32 s0, s24, 9599
	s_mov_b32 s21, s0
	s_mov_b32 s0, s21
	s_cmpk_lt_u32 s0, 9600
	s_cbranch_scc0 .Ltc2_c67
	s_and_b32 s1, s0, 31
	s_lshl_b32 s1, s1, 6
	s_lshr_b32 s21, s0, 5
	s_lshl_b32 s21, s21, 6
	s_movk_i32 s29, 64
	s_cmpk_lt_u32 s21, 7680
	s_cbranch_scc1 .Ltc2_n69
	s_cmpk_lt_u32 s21, 18944
	s_cbranch_scc0 .Ltc2_t68
	s_add_u32 s21, s21, 48
	s_branch .Ltc2_n69

; __device__ __forceinline__ void tconv_tile(LAS float* tile, const float* src, int ld, int k0, int n0, int mode, bf16_t* dst, int K) {
;     ...
;     for (int it = 0; it < 2; ++it) { const int idx = tid + it * 512, kk = idx >> 4, n4 = (idx & 15) * 4, nn = n0 + n4; int oc = nn; bool valid = true;
;         if (mode == 1) { if (nn < 7680) oc = nn; else if (nn < 18944) oc = nn + 48; else if (nn < INW) oc = 7680 + (nn - 18944); else valid = false; }
;         f32x4 v = (f32x4){0.f, 0.f, 0.f, 0.f}; if (valid) v = *(const f32x4*)(src + (size_t)(k0 + kk) * ld + oc);
;         tile[kk * 65 + n4 + 0] = v[0]; tile[kk * 65 + n4 + 1] = v[1]; tile[kk * 65 + n4 + 2] = v[2]; tile[kk * 65 + n4 + 3] = v[3]; }
;     __syncthreads();
.Ltc2_d66:
	v_mov_b32_e32 v86, 0
	v_mov_b32_e32 v87, 0
	v_mov_b32_e32 v88, 0
	v_mov_b32_e32 v89, 0
	v_mov_b32_e32 v90, 0
	v_mov_b32_e32 v91, 0
	v_mov_b32_e32 v92, 0
	v_mov_b32_e32 v93, 0
	v_mul_u32_u24_e32 v26, s28, v20
	v_add_lshl_u32 v26, v26, v21, 2
	s_lshl_b32 s0, s28, 7
	v_add_u32_e32 v27, s0, v26
	v_cmp_gt_i32_e32 vcc, s29, v21
	s_and_saveexec_b64 s[0:1], vcc
	global_load_dwordx4 v[86:89], v26, s[26:27]
	global_load_dwordx4 v[90:93], v27, s[26:27]
	s_mov_b64 exec, s[0:1]
	s_add_u32 s24, s24, 0xe0
	s_cmpk_ge_u32 s25, 9600
	s_cbranch_scc1 .Ltc2_exit
	s_waitcnt vmcnt(10)
	v_add_u32_e32 v28, 0, v22
	ds_write2_b32 v28, v34, v35 offset1:1
	ds_write2_b32 v28, v36, v37 offset0:2 offset1:3
	v_add_u32_e32 v28, 0x2080, v28
	ds_write2_b32 v28, v38, v39 offset1:1
	ds_write2_b32 v28, v40, v41 offset0:2 offset1:3
	s_mov_b32 s21, s25
	s_mov_b32 s0, s21
	s_cmpk_lt_u32 s0, 9600
	s_cbranch_scc0 .Ltc2_c80
	s_and_b32 s1, s0, 31
	s_lshl_b32 s1, s1, 6
	s_lshr_b32 s21, s0, 5
	s_lshl_b32 s21, s21, 17
	s_add_u32 s1, s1, s21
	s_lshl_b32 s1, s1, 1
	s_add_u32 s1, s1, 0x4001000
	s_add_u32 s30, s68, s1
	s_addc_u32 s31, s69, 0
	s_movk_i32 s20, 0x800
	s_branch .Ltc2_d79

; __device__ __forceinline__ unsigned cvt_pk_bf16(float lo, float hi) { unsigned r; asm("v_cvt_pk_bf16_f32 %0, %1, %2" : "=v"(r) : "v"(lo), "v"(hi)); return r; }
; __device__ __forceinline__ void tconv_tile(LAS float* tile, const float* src, int ld, int k0, int n0, int mode, bf16_t* dst, int K) {
;     ...
;     { const int n = tid >> 3, k8 = (tid & 7) * 8; float v[8];
; #pragma unroll
;         for (int e = 0; e < 8; ++e) v[e] = tile[(k8 + e) * 65 + n];
;         u32x4 w; w.x = cvt_pk_bf16(v[0], v[1]); w.y = cvt_pk_bf16(v[2], v[3]); w.z = cvt_pk_bf16(v[4], v[5]); w.w = cvt_pk_bf16(v[6], v[7]);
;         *(u32x4*)(dst + (size_t)(n0 + n) * K + k0 + k8) = w; }
;     __syncthreads();
.Ltc2_d79:
	v_mul_u32_u24_e32 v29, s20, v24
	v_add_lshl_u32 v29, v29, v25, 1
	s_waitcnt lgkmcnt(0)
	s_barrier
	v_add_u32_e32 v28, 0, v23
	ds_read2_b32 v[2:3], v28 offset1:65
	ds_read2_b32 v[4:5], v28 offset0:130 offset1:195
	v_add_u32_e32 v28, 0x400, v28
	ds_read2_b32 v[6:7], v28 offset0:4 offset1:69
	ds_read2_b32 v[10:11], v28 offset0:134 offset1:199
	s_waitcnt lgkmcnt(3)
	v_cvt_pk_bf16_f32 v2, v2, v3
	s_waitcnt lgkmcnt(2)
	v_cvt_pk_bf16_f32 v3, v4, v5
	s_waitcnt lgkmcnt(1)
	v_cvt_pk_bf16_f32 v4, v6, v7
	s_waitcnt lgkmcnt(0)
	v_cvt_pk_bf16_f32 v5, v10, v11
	global_store_dwordx4 v29, v[2:5], s[30:31]
	s_add_u32 s25, s25, 0xe0
	s_min_u32 s0, s24, 9599
	s_mov_b32 s21, s0
	s_mov_b32 s0, s21
	s_cmpk_lt_u32 s0, 9600
	s_cbranch_scc0 .Ltc2_c87
	s_and_b32 s1, s0, 31
	s_lshl_b32 s1, s1, 6
	s_lshr_b32 s21, s0, 5
	s_lshl_b32 s21, s21, 6
	s_movk_i32 s29, 64
	s_cmpk_lt_u32 s21, 7680
	s_cbranch_scc1 .Ltc2_n89
	s_cmpk_lt_u32 s21, 18944
	s_cbranch_scc0 .Ltc2_t88
	s_add_u32 s21, s21, 48
	s_branch .Ltc2_n89

; __device__ __forceinline__ unsigned cvt_pk_bf16(float lo, float hi) { unsigned r; asm("v_cvt_pk_bf16_f32 %0, %1, %2" : "=v"(r) : "v"(lo), "v"(hi)); return r; }
; __device__ __forceinline__ void tconv_tile(LAS float* tile, const float* src, int ld, int k0, int n0, int mode, bf16_t* dst, int K) {
;     ...
;     for (int it = 0; it < 2; ++it) { const int idx = tid + it * 512, kk = idx >> 4, n4 = (idx & 15) * 4, nn = n0 + n4; int oc = nn; bool valid = true;
;         if (mode == 1) { if (nn < 7680) oc = nn; else if (nn < 18944) oc = nn + 48; else if (nn < INW) oc = 7680 + (nn - 18944); else valid = false; }
;         f32x4 v = (f32x4){0.f, 0.f, 0.f, 0.f}; if (valid) v = *(const f32x4*)(src + (size_t)(k0 + kk) * ld + oc);
;         tile[kk * 65 + n4 + 0] = v[0]; tile[kk * 65 + n4 + 1] = v[1]; tile[kk * 65 + n4 + 2] = v[2]; tile[kk * 65 + n4 + 3] = v[3]; }
;     __syncthreads();
;     { const int n = tid >> 3, k8 = (tid & 7) * 8; float v[8];
; #pragma unroll
;         for (int e = 0; e < 8; ++e) v[e] = tile[(k8 + e) * 65 + n];
;         u32x4 w; w.x = cvt_pk_bf16(v[0], v[1]); w.y = cvt_pk_bf16(v[2], v[3]); w.z = cvt_pk_bf16(v[4], v[5]); w.w = cvt_pk_bf16(v[6], v[7]);
;         *(u32x4*)(dst + (size_t)(n0 + n) * K + k0 + k8) = w; }
;     __syncthreads();
.Ltc2_d86:
	v_mov_b32_e32 v34, 0
	v_mov_b32_e32 v35, 0
	v_mov_b32_e32 v36, 0
	v_mov_b32_e32 v37, 0
	v_mov_b32_e32 v38, 0
	v_mov_b32_e32 v39, 0
	v_mov_b32_e32 v40, 0
	v_mov_b32_e32 v41, 0
	v_mul_u32_u24_e32 v26, s28, v20
	v_add_lshl_u32 v26, v26, v21, 2
	s_lshl_b32 s0, s28, 7
	v_add_u32_e32 v27, s0, v26
	v_cmp_gt_i32_e32 vcc, s29, v21
	s_and_saveexec_b64 s[0:1], vcc
	global_load_dwordx4 v[34:37], v26, s[26:27]
	global_load_dwordx4 v[38:41], v27, s[26:27]
	s_mov_b64 exec, s[0:1]
	s_add_u32 s24, s24, 0xe0
	s_cmpk_ge_u32 s25, 9600
	s_cbranch_scc1 .Ltc2_exit
	s_waitcnt vmcnt(11)
	v_add_u32_e32 v28, 16896, v22
	ds_write2_b32 v28, v42, v43 offset1:1
	ds_write2_b32 v28, v44, v45 offset0:2 offset1:3
	v_add_u32_e32 v28, 0x2080, v28
	ds_write2_b32 v28, v46, v47 offset1:1
	ds_write2_b32 v28, v48, v49 offset0:2 offset1:3
	s_mov_b32 s21, s25
	s_mov_b32 s0, s21
	s_cmpk_lt_u32 s0, 9600
	s_cbranch_scc0 .Ltc2_c100
	s_and_b32 s1, s0, 31
	s_lshl_b32 s1, s1, 6
	s_lshr_b32 s21, s0, 5
	s_lshl_b32 s21, s21, 17
	s_add_u32 s1, s1, s21
	s_lshl_b32 s1, s1, 1
	s_add_u32 s1, s1, 0x4001000
	s_add_u32 s30, s68, s1
	s_addc_u32 s31, s69, 0
	s_movk_i32 s20, 0x800
	s_branch .Ltc2_d99

; __device__ __forceinline__ unsigned cvt_pk_bf16(float lo, float hi) { unsigned r; asm("v_cvt_pk_bf16_f32 %0, %1, %2" : "=v"(r) : "v"(lo), "v"(hi)); return r; }
; __device__ __forceinline__ void tconv_tile(LAS float* tile, const float* src, int ld, int k0, int n0, int mode, bf16_t* dst, int K) {
;     ...
;     { const int n = tid >> 3, k8 = (tid & 7) * 8; float v[8];
; #pragma unroll
;         for (int e = 0; e < 8; ++e) v[e] = tile[(k8 + e) * 65 + n];
;         u32x4 w; w.x = cvt_pk_bf16(v[0], v[1]); w.y = cvt_pk_bf16(v[2], v[3]); w.z = cvt_pk_bf16(v[4], v[5]); w.w = cvt_pk_bf16(v[6], v[7]);
;         *(u32x4*)(dst + (size_t)(n0 + n) * K + k0 + k8) = w; }
;     __syncthreads();
.Ltc2_d99:
	v_mul_u32_u24_e32 v29, s20, v24
	v_add_lshl_u32 v29, v29, v25, 1
	s_waitcnt lgkmcnt(0)
	s_barrier
	v_add_u32_e32 v28, 16896, v23
	ds_read2_b32 v[2:3], v28 offset1:65
	ds_read2_b32 v[4:5], v28 offset0:130 offset1:195
	v_add_u32_e32 v28, 0x400, v28
	ds_read2_b32 v[6:7], v28 offset0:4 offset1:69
	ds_read2_b32 v[10:11], v28 offset0:134 offset1:199
	s_waitcnt lgkmcnt(3)
	v_cvt_pk_bf16_f32 v2, v2, v3
	s_waitcnt lgkmcnt(2)
	v_cvt_pk_bf16_f32 v3, v4, v5
	s_waitcnt lgkmcnt(1)
	v_cvt_pk_bf16_f32 v4, v6, v7
	s_waitcnt lgkmcnt(0)
	v_cvt_pk_bf16_f32 v5, v10, v11
	global_store_dwordx4 v29, v[2:5], s[30:31]
	s_add_u32 s25, s25, 0xe0
	s_min_u32 s0, s24, 9599
	s_mov_b32 s21, s0
	s_mov_b32 s0, s21
	s_cmpk_lt_u32 s0, 9600
	s_cbranch_scc0 .Ltc2_c107
	s_and_b32 s1, s0, 31
	s_lshl_b32 s1, s1, 6
	s_lshr_b32 s21, s0, 5
	s_lshl_b32 s21, s21, 6
	s_movk_i32 s29, 64
	s_cmpk_lt_u32 s21, 7680
	s_cbranch_scc1 .Ltc2_n109
	s_cmpk_lt_u32 s21, 18944
	s_cbranch_scc0 .Ltc2_t108
	s_add_u32 s21, s21, 48
	s_branch .Ltc2_n109

; __device__ __forceinline__ unsigned cvt_pk_bf16(float lo, float hi) { unsigned r; asm("v_cvt_pk_bf16_f32 %0, %1, %2" : "=v"(r) : "v"(lo), "v"(hi)); return r; }
; __device__ __forceinline__ void tconv_tile(LAS float* tile, const float* src, int ld, int k0, int n0, int mode, bf16_t* dst, int K) {
;     ...
;     for (int it = 0; it < 2; ++it) { const int idx = tid + it * 512, kk = idx >> 4, n4 = (idx & 15) * 4, nn = n0 + n4; int oc = nn; bool valid = true;
;         if (mode == 1) { if (nn < 7680) oc = nn; else if (nn < 18944) oc = nn + 48; else if (nn < INW) oc = 7680 + (nn - 18944); else valid = false; }
;         f32x4 v = (f32x4){0.f, 0.f, 0.f, 0.f}; if (valid) v = *(const f32x4*)(src + (size_t)(k0 + kk) * ld + oc);
;         tile[kk * 65 + n4 + 0] = v[0]; tile[kk * 65 + n4 + 1] = v[1]; tile[kk * 65 + n4 + 2] = v[2]; tile[kk * 65 + n4 + 3] = v[3]; }
;     __syncthreads();
;     { const int n = tid >> 3, k8 = (tid & 7) * 8; float v[8];
; #pragma unroll
;         for (int e = 0; e < 8; ++e) v[e] = tile[(k8 + e) * 65 + n];
;         u32x4 w; w.x = cvt_pk_bf16(v[0], v[1]); w.y = cvt_pk_bf16(v[2], v[3]); w.z = cvt_pk_bf16(v[4], v[5]); w.w = cvt_pk_bf16(v[6], v[7]);
;         *(u32x4*)(dst + (size_t)(n0 + n) * K + k0 + k8) = w; }
;     __syncthreads();
.Ltc2_d106:
	v_mov_b32_e32 v42, 0
	v_mov_b32_e32 v43, 0
	v_mov_b32_e32 v44, 0
	v_mov_b32_e32 v45, 0
	v_mov_b32_e32 v46, 0
	v_mov_b32_e32 v47, 0
	v_mov_b32_e32 v48, 0
	v_mov_b32_e32 v49, 0
	v_mul_u32_u24_e32 v26, s28, v20
	v_add_lshl_u32 v26, v26, v21, 2
	s_lshl_b32 s0, s28, 7
	v_add_u32_e32 v27, s0, v26
	v_cmp_gt_i32_e32 vcc, s29, v21
	s_and_saveexec_b64 s[0:1], vcc
	global_load_dwordx4 v[42:45], v26, s[26:27]
	global_load_dwordx4 v[46:49], v27, s[26:27]
	s_mov_b64 exec, s[0:1]
	s_add_u32 s24, s24, 0xe0
	s_cmpk_ge_u32 s25, 9600
	s_cbranch_scc1 .Ltc2_exit
	s_waitcnt vmcnt(12)
	v_add_u32_e32 v28, 0, v22
	ds_write2_b32 v28, v50, v51 offset1:1
	ds_write2_b32 v28, v52, v53 offset0:2 offset1:3
	v_add_u32_e32 v28, 0x2080, v28
	ds_write2_b32 v28, v54, v55 offset1:1
	ds_write2_b32 v28, v56, v57 offset0:2 offset1:3
	s_mov_b32 s21, s25
	s_mov_b32 s0, s21
	s_cmpk_lt_u32 s0, 9600
	s_cbranch_scc0 .Ltc2_c120
	s_and_b32 s1, s0, 31
	s_lshl_b32 s1, s1, 6
	s_lshr_b32 s21, s0, 5
	s_lshl_b32 s21, s21, 17
	s_add_u32 s1, s1, s21
	s_lshl_b32 s1, s1, 1
	s_add_u32 s1, s1, 0x4001000
	s_add_u32 s30, s68, s1
	s_addc_u32 s31, s69, 0
	s_movk_i32 s20, 0x800
	s_branch .Ltc2_d119

; __device__ __forceinline__ unsigned cvt_pk_bf16(float lo, float hi) { unsigned r; asm("v_cvt_pk_bf16_f32 %0, %1, %2" : "=v"(r) : "v"(lo), "v"(hi)); return r; }
; __device__ __forceinline__ void tconv_tile(LAS float* tile, const float* src, int ld, int k0, int n0, int mode, bf16_t* dst, int K) {
;     ...
;     for (int it = 0; it < 2; ++it) { const int idx = tid + it * 512, kk = idx >> 4, n4 = (idx & 15) * 4, nn = n0 + n4; int oc = nn; bool valid = true;
;         if (mode == 1) { if (nn < 7680) oc = nn; else if (nn < 18944) oc = nn + 48; else if (nn < INW) oc = 7680 + (nn - 18944); else valid = false; }
;         f32x4 v = (f32x4){0.f, 0.f, 0.f, 0.f}; if (valid) v = *(const f32x4*)(src + (size_t)(k0 + kk) * ld + oc);
;         tile[kk * 65 + n4 + 0] = v[0]; tile[kk * 65 + n4 + 1] = v[1]; tile[kk * 65 + n4 + 2] = v[2]; tile[kk * 65 + n4 + 3] = v[3]; }
;     __syncthreads();
;     { const int n = tid >> 3, k8 = (tid & 7) * 8; float v[8];
; #pragma unroll
;         for (int e = 0; e < 8; ++e) v[e] = tile[(k8 + e) * 65 + n];
;         u32x4 w; w.x = cvt_pk_bf16(v[0], v[1]); w.y = cvt_pk_bf16(v[2], v[3]); w.z = cvt_pk_bf16(v[4], v[5]); w.w = cvt_pk_bf16(v[6], v[7]);
;         *(u32x4*)(dst + (size_t)(n0 + n) * K + k0 + k8) = w; }
;     __syncthreads();
.Ltc2_d126:
	v_mov_b32_e32 v50, 0
	v_mov_b32_e32 v51, 0
	v_mov_b32_e32 v52, 0
	v_mov_b32_e32 v53, 0
	v_mov_b32_e32 v54, 0
	v_mov_b32_e32 v55, 0
	v_mov_b32_e32 v56, 0
	v_mov_b32_e32 v57, 0
	v_mul_u32_u24_e32 v26, s28, v20
	v_add_lshl_u32 v26, v26, v21, 2
	s_lshl_b32 s0, s28, 7
	v_add_u32_e32 v27, s0, v26
	v_cmp_gt_i32_e32 vcc, s29, v21
	s_and_saveexec_b64 s[0:1], vcc
	global_load_dwordx4 v[50:53], v26, s[26:27]
	global_load_dwordx4 v[54:57], v27, s[26:27]
	s_mov_b64 exec, s[0:1]
	s_add_u32 s24, s24, 0xe0
	s_cmpk_ge_u32 s25, 9600
	s_cbranch_scc1 .Ltc2_exit
	s_waitcnt vmcnt(13)
	v_add_u32_e32 v28, 16896, v22
	ds_write2_b32 v28, v58, v59 offset1:1
	ds_write2_b32 v28, v60, v61 offset0:2 offset1:3
	v_add_u32_e32 v28, 0x2080, v28
	ds_write2_b32 v28, v62, v63 offset1:1
	ds_write2_b32 v28, v64, v65 offset0:2 offset1:3
	s_mov_b32 s21, s25
	s_mov_b32 s0, s21
	s_cmpk_lt_u32 s0, 9600
	s_cbranch_scc0 .Ltc2_c140
	s_and_b32 s1, s0, 31
	s_lshl_b32 s1, s1, 6
	s_lshr_b32 s21, s0, 5
	s_lshl_b32 s21, s21, 17
	s_add_u32 s1, s1, s21
	s_lshl_b32 s1, s1, 1
	s_add_u32 s1, s1, 0x4001000
	s_add_u32 s30, s68, s1
	s_addc_u32 s31, s69, 0
	s_movk_i32 s20, 0x800
	s_branch .Ltc2_d139

; __device__ __forceinline__ unsigned cvt_pk_bf16(float lo, float hi) { unsigned r; asm("v_cvt_pk_bf16_f32 %0, %1, %2" : "=v"(r) : "v"(lo), "v"(hi)); return r; }
; __device__ __forceinline__ void tconv_tile(LAS float* tile, const float* src, int ld, int k0, int n0, int mode, bf16_t* dst, int K) {
;     ...
;     for (int it = 0; it < 2; ++it) { const int idx = tid + it * 512, kk = idx >> 4, n4 = (idx & 15) * 4, nn = n0 + n4; int oc = nn; bool valid = true;
;         if (mode == 1) { if (nn < 7680) oc = nn; else if (nn < 18944) oc = nn + 48; else if (nn < INW) oc = 7680 + (nn - 18944); else valid = false; }
;         f32x4 v = (f32x4){0.f, 0.f, 0.f, 0.f}; if (valid) v = *(const f32x4*)(src + (size_t)(k0 + kk) * ld + oc);
;         tile[kk * 65 + n4 + 0] = v[0]; tile[kk * 65 + n4 + 1] = v[1]; tile[kk * 65 + n4 + 2] = v[2]; tile[kk * 65 + n4 + 3] = v[3]; }
;     __syncthreads();
;     { const int n = tid >> 3, k8 = (tid & 7) * 8; float v[8];
; #pragma unroll
;         for (int e = 0; e < 8; ++e) v[e] = tile[(k8 + e) * 65 + n];
;         u32x4 w; w.x = cvt_pk_bf16(v[0], v[1]); w.y = cvt_pk_bf16(v[2], v[3]); w.z = cvt_pk_bf16(v[4], v[5]); w.w = cvt_pk_bf16(v[6], v[7]);
;         *(u32x4*)(dst + (size_t)(n0 + n) * K + k0 + k8) = w; }
;     __syncthreads();
.Ltc2_d146:
	v_mov_b32_e32 v58, 0
	v_mov_b32_e32 v59, 0
	v_mov_b32_e32 v60, 0
	v_mov_b32_e32 v61, 0
	v_mov_b32_e32 v62, 0
	v_mov_b32_e32 v63, 0
	v_mov_b32_e32 v64, 0
	v_mov_b32_e32 v65, 0
	v_mul_u32_u24_e32 v26, s28, v20
	v_add_lshl_u32 v26, v26, v21, 2
	s_lshl_b32 s0, s28, 7
	v_add_u32_e32 v27, s0, v26
	v_cmp_gt_i32_e32 vcc, s29, v21
	s_and_saveexec_b64 s[0:1], vcc
	global_load_dwordx4 v[58:61], v26, s[26:27]
	global_load_dwordx4 v[62:65], v27, s[26:27]
	s_mov_b64 exec, s[0:1]
	s_add_u32 s24, s24, 0xe0
	s_cmpk_ge_u32 s25, 9600
	s_cbranch_scc1 .Ltc2_exit
	s_waitcnt vmcnt(14)
	v_add_u32_e32 v28, 0, v22
	ds_write2_b32 v28, v78, v79 offset1:1
	ds_write2_b32 v28, v80, v81 offset0:2 offset1:3
	v_add_u32_e32 v28, 0x2080, v28
	ds_write2_b32 v28, v82, v83 offset1:1
	ds_write2_b32 v28, v84, v85 offset0:2 offset1:3
	s_mov_b32 s21, s25
	s_mov_b32 s0, s21
	s_cmpk_lt_u32 s0, 9600
	s_cbranch_scc0 .Ltc2_c160
	s_and_b32 s1, s0, 31
	s_lshl_b32 s1, s1, 6
	s_lshr_b32 s21, s0, 5
	s_lshl_b32 s21, s21, 17
	s_add_u32 s1, s1, s21
	s_lshl_b32 s1, s1, 1
	s_add_u32 s1, s1, 0x4001000
	s_add_u32 s30, s68, s1
	s_addc_u32 s31, s69, 0
	s_movk_i32 s20, 0x800
	s_branch .Ltc2_d159

; __device__ __forceinline__ unsigned cvt_pk_bf16(float lo, float hi) { unsigned r; asm("v_cvt_pk_bf16_f32 %0, %1, %2" : "=v"(r) : "v"(lo), "v"(hi)); return r; }
; __device__ __forceinline__ void tconv_tile(LAS float* tile, const float* src, int ld, int k0, int n0, int mode, bf16_t* dst, int K) {
;     ...
;     for (int it = 0; it < 2; ++it) { const int idx = tid + it * 512, kk = idx >> 4, n4 = (idx & 15) * 4, nn = n0 + n4; int oc = nn; bool valid = true;
;         if (mode == 1) { if (nn < 7680) oc = nn; else if (nn < 18944) oc = nn + 48; else if (nn < INW) oc = 7680 + (nn - 18944); else valid = false; }
;         f32x4 v = (f32x4){0.f, 0.f, 0.f, 0.f}; if (valid) v = *(const f32x4*)(src + (size_t)(k0 + kk) * ld + oc);
;         tile[kk * 65 + n4 + 0] = v[0]; tile[kk * 65 + n4 + 1] = v[1]; tile[kk * 65 + n4 + 2] = v[2]; tile[kk * 65 + n4 + 3] = v[3]; }
;     __syncthreads();
;     { const int n = tid >> 3, k8 = (tid & 7) * 8; float v[8];
; #pragma unroll
;         for (int e = 0; e < 8; ++e) v[e] = tile[(k8 + e) * 65 + n];
;         u32x4 w; w.x = cvt_pk_bf16(v[0], v[1]); w.y = cvt_pk_bf16(v[2], v[3]); w.z = cvt_pk_bf16(v[4], v[5]); w.w = cvt_pk_bf16(v[6], v[7]);
;         *(u32x4*)(dst + (size_t)(n0 + n) * K + k0 + k8) = w; }
;     __syncthreads();
.Ltc2_d166:
	v_mov_b32_e32 v78, 0
	v_mov_b32_e32 v79, 0
	v_mov_b32_e32 v80, 0
	v_mov_b32_e32 v81, 0
	v_mov_b32_e32 v82, 0
	v_mov_b32_e32 v83, 0
	v_mov_b32_e32 v84, 0
	v_mov_b32_e32 v85, 0
	v_mul_u32_u24_e32 v26, s28, v20
	v_add_lshl_u32 v26, v26, v21, 2
	s_lshl_b32 s0, s28, 7
	v_add_u32_e32 v27, s0, v26
	v_cmp_gt_i32_e32 vcc, s29, v21
	s_and_saveexec_b64 s[0:1], vcc
	global_load_dwordx4 v[78:81], v26, s[26:27]
	global_load_dwordx4 v[82:85], v27, s[26:27]
	s_mov_b64 exec, s[0:1]
	s_add_u32 s24, s24, 0xe0
	s_cmpk_ge_u32 s25, 9600
	s_cbranch_scc1 .Ltc2_exit
	s_waitcnt vmcnt(15)
	v_add_u32_e32 v28, 16896, v22
	ds_write2_b32 v28, v86, v87 offset1:1
	ds_write2_b32 v28, v88, v89 offset0:2 offset1:3
	v_add_u32_e32 v28, 0x2080, v28
	ds_write2_b32 v28, v90, v91 offset1:1
	ds_write2_b32 v28, v92, v93 offset0:2 offset1:3
	s_mov_b32 s21, s25
	s_mov_b32 s0, s21
	s_cmpk_lt_u32 s0, 9600
	s_cbranch_scc0 .Ltc2_c180
	s_and_b32 s1, s0, 31
	s_lshl_b32 s1, s1, 6
	s_lshr_b32 s21, s0, 5
	s_lshl_b32 s21, s21, 17
	s_add_u32 s1, s1, s21
	s_lshl_b32 s1, s1, 1
	s_add_u32 s1, s1, 0x4001000
	s_add_u32 s30, s68, s1
	s_addc_u32 s31, s69, 0
	s_movk_i32 s20, 0x800
	s_branch .Ltc2_d179

; __device__ __forceinline__ unsigned cvt_pk_bf16(float lo, float hi) { unsigned r; asm("v_cvt_pk_bf16_f32 %0, %1, %2" : "=v"(r) : "v"(lo), "v"(hi)); return r; }
; __device__ __forceinline__ void tconv_tile(LAS float* tile, const float* src, int ld, int k0, int n0, int mode, bf16_t* dst, int K) {
;     ...
;     for (int it = 0; it < 2; ++it) { const int idx = tid + it * 512, kk = idx >> 4, n4 = (idx & 15) * 4, nn = n0 + n4; int oc = nn; bool valid = true;
;         if (mode == 1) { if (nn < 7680) oc = nn; else if (nn < 18944) oc = nn + 48; else if (nn < INW) oc = 7680 + (nn - 18944); else valid = false; }
;         f32x4 v = (f32x4){0.f, 0.f, 0.f, 0.f}; if (valid) v = *(const f32x4*)(src + (size_t)(k0 + kk) * ld + oc);
;         tile[kk * 65 + n4 + 0] = v[0]; tile[kk * 65 + n4 + 1] = v[1]; tile[kk * 65 + n4 + 2] = v[2]; tile[kk * 65 + n4 + 3] = v[3]; }
;     __syncthreads();
;     { const int n = tid >> 3, k8 = (tid & 7) * 8; float v[8];
; #pragma unroll
;         for (int e = 0; e < 8; ++e) v[e] = tile[(k8 + e) * 65 + n];
;         u32x4 w; w.x = cvt_pk_bf16(v[0], v[1]); w.y = cvt_pk_bf16(v[2], v[3]); w.z = cvt_pk_bf16(v[4], v[5]); w.w = cvt_pk_bf16(v[6], v[7]);
;         *(u32x4*)(dst + (size_t)(n0 + n) * K + k0 + k8) = w; }
;     __syncthreads();
.Ltc2_d186:
	v_mov_b32_e32 v86, 0
	v_mov_b32_e32 v87, 0
	v_mov_b32_e32 v88, 0
	v_mov_b32_e32 v89, 0
	v_mov_b32_e32 v90, 0
	v_mov_b32_e32 v91, 0
	v_mov_b32_e32 v92, 0
	v_mov_b32_e32 v93, 0
	v_mul_u32_u24_e32 v26, s28, v20
	v_add_lshl_u32 v26, v26, v21, 2
	s_lshl_b32 s0, s28, 7
	v_add_u32_e32 v27, s0, v26
	v_cmp_gt_i32_e32 vcc, s29, v21
	s_and_saveexec_b64 s[0:1], vcc
	global_load_dwordx4 v[86:89], v26, s[26:27]
	global_load_dwordx4 v[90:93], v27, s[26:27]
	s_mov_b64 exec, s[0:1]
	s_add_u32 s24, s24, 0xe0
.Ltc2_loop:
	s_cmpk_ge_u32 s25, 9600
	s_cbranch_scc1 .Ltc2_exit
	s_waitcnt vmcnt(15)
	v_add_u32_e32 v28, 0, v22
	ds_write2_b32 v28, v34, v35 offset1:1
	ds_write2_b32 v28, v36, v37 offset0:2 offset1:3
	v_add_u32_e32 v28, 0x2080, v28
	ds_write2_b32 v28, v38, v39 offset1:1
	ds_write2_b32 v28, v40, v41 offset0:2 offset1:3
	s_mov_b32 s21, s25
	s_mov_b32 s0, s21
	s_cmpk_lt_u32 s0, 9600
	s_cbranch_scc0 .Ltc2_c200
	s_and_b32 s1, s0, 31
	s_lshl_b32 s1, s1, 6
	s_lshr_b32 s21, s0, 5
	s_lshl_b32 s21, s21, 17
	s_add_u32 s1, s1, s21
	s_lshl_b32 s1, s1, 1
	s_add_u32 s1, s1, 0x4001000
	s_add_u32 s30, s68, s1
	s_addc_u32 s31, s69, 0
	s_movk_i32 s20, 0x800
	s_branch .Ltc2_d199

; __device__ __forceinline__ unsigned cvt_pk_bf16(float lo, float hi) { unsigned r; asm("v_cvt_pk_bf16_f32 %0, %1, %2" : "=v"(r) : "v"(lo), "v"(hi)); return r; }
; __device__ __forceinline__ void tconv_tile(LAS float* tile, const float* src, int ld, int k0, int n0, int mode, bf16_t* dst, int K) {
;     ...
;     for (int it = 0; it < 2; ++it) { const int idx = tid + it * 512, kk = idx >> 4, n4 = (idx & 15) * 4, nn = n0 + n4; int oc = nn; bool valid = true;
;         if (mode == 1) { if (nn < 7680) oc = nn; else if (nn < 18944) oc = nn + 48; else if (nn < INW) oc = 7680 + (nn - 18944); else valid = false; }
;         f32x4 v = (f32x4){0.f, 0.f, 0.f, 0.f}; if (valid) v = *(const f32x4*)(src + (size_t)(k0 + kk) * ld + oc);
;         tile[kk * 65 + n4 + 0] = v[0]; tile[kk * 65 + n4 + 1] = v[1]; tile[kk * 65 + n4 + 2] = v[2]; tile[kk * 65 + n4 + 3] = v[3]; }
;     __syncthreads();
;     { const int n = tid >> 3, k8 = (tid & 7) * 8; float v[8];
; #pragma unroll
;         for (int e = 0; e < 8; ++e) v[e] = tile[(k8 + e) * 65 + n];
;         u32x4 w; w.x = cvt_pk_bf16(v[0], v[1]); w.y = cvt_pk_bf16(v[2], v[3]); w.z = cvt_pk_bf16(v[4], v[5]); w.w = cvt_pk_bf16(v[6], v[7]);
;         *(u32x4*)(dst + (size_t)(n0 + n) * K + k0 + k8) = w; }
;     __syncthreads();
.Ltc2_d206:
	v_mov_b32_e32 v34, 0
	v_mov_b32_e32 v35, 0
	v_mov_b32_e32 v36, 0
	v_mov_b32_e32 v37, 0
	v_mov_b32_e32 v38, 0
	v_mov_b32_e32 v39, 0
	v_mov_b32_e32 v40, 0
	v_mov_b32_e32 v41, 0
	v_mul_u32_u24_e32 v26, s28, v20
	v_add_lshl_u32 v26, v26, v21, 2
	s_lshl_b32 s0, s28, 7
	v_add_u32_e32 v27, s0, v26
	v_cmp_gt_i32_e32 vcc, s29, v21
	s_and_saveexec_b64 s[0:1], vcc
	global_load_dwordx4 v[34:37], v26, s[26:27]
	global_load_dwordx4 v[38:41], v27, s[26:27]
	s_mov_b64 exec, s[0:1]
	s_add_u32 s24, s24, 0xe0
	s_cmpk_ge_u32 s25, 9600
	s_cbranch_scc1 .Ltc2_exit
	s_waitcnt vmcnt(15)
	v_add_u32_e32 v28, 16896, v22
	ds_write2_b32 v28, v42, v43 offset1:1
	ds_write2_b32 v28, v44, v45 offset0:2 offset1:3
	v_add_u32_e32 v28, 0x2080, v28
	ds_write2_b32 v28, v46, v47 offset1:1
	ds_write2_b32 v28, v48, v49 offset0:2 offset1:3
	s_mov_b32 s21, s25
	s_mov_b32 s0, s21
	s_cmpk_lt_u32 s0, 9600
	s_cbranch_scc0 .Ltc2_c220
	s_and_b32 s1, s0, 31
	s_lshl_b32 s1, s1, 6
	s_lshr_b32 s21, s0, 5
	s_lshl_b32 s21, s21, 17
	s_add_u32 s1, s1, s21
	s_lshl_b32 s1, s1, 1
	s_add_u32 s1, s1, 0x4001000
	s_add_u32 s30, s68, s1
	s_addc_u32 s31, s69, 0
	s_movk_i32 s20, 0x800
	s_branch .Ltc2_d219

; __device__ __forceinline__ unsigned cvt_pk_bf16(float lo, float hi) { unsigned r; asm("v_cvt_pk_bf16_f32 %0, %1, %2" : "=v"(r) : "v"(lo), "v"(hi)); return r; }
; __device__ __forceinline__ void tconv_tile(LAS float* tile, const float* src, int ld, int k0, int n0, int mode, bf16_t* dst, int K) {
;     ...
;     for (int it = 0; it < 2; ++it) { const int idx = tid + it * 512, kk = idx >> 4, n4 = (idx & 15) * 4, nn = n0 + n4; int oc = nn; bool valid = true;
;         if (mode == 1) { if (nn < 7680) oc = nn; else if (nn < 18944) oc = nn + 48; else if (nn < INW) oc = 7680 + (nn - 18944); else valid = false; }
;         f32x4 v = (f32x4){0.f, 0.f, 0.f, 0.f}; if (valid) v = *(const f32x4*)(src + (size_t)(k0 + kk) * ld + oc);
;         tile[kk * 65 + n4 + 0] = v[0]; tile[kk * 65 + n4 + 1] = v[1]; tile[kk * 65 + n4 + 2] = v[2]; tile[kk * 65 + n4 + 3] = v[3]; }
;     __syncthreads();
;     { const int n = tid >> 3, k8 = (tid & 7) * 8; float v[8];
; #pragma unroll
;         for (int e = 0; e < 8; ++e) v[e] = tile[(k8 + e) * 65 + n];
;         u32x4 w; w.x = cvt_pk_bf16(v[0], v[1]); w.y = cvt_pk_bf16(v[2], v[3]); w.z = cvt_pk_bf16(v[4], v[5]); w.w = cvt_pk_bf16(v[6], v[7]);
;         *(u32x4*)(dst + (size_t)(n0 + n) * K + k0 + k8) = w; }
;     __syncthreads();
.Ltc2_d226:
	v_mov_b32_e32 v42, 0
	v_mov_b32_e32 v43, 0
	v_mov_b32_e32 v44, 0
	v_mov_b32_e32 v45, 0
	v_mov_b32_e32 v46, 0
	v_mov_b32_e32 v47, 0
	v_mov_b32_e32 v48, 0
	v_mov_b32_e32 v49, 0
	v_mul_u32_u24_e32 v26, s28, v20
	v_add_lshl_u32 v26, v26, v21, 2
	s_lshl_b32 s0, s28, 7
	v_add_u32_e32 v27, s0, v26
	v_cmp_gt_i32_e32 vcc, s29, v21
	s_and_saveexec_b64 s[0:1], vcc
	global_load_dwordx4 v[42:45], v26, s[26:27]
	global_load_dwordx4 v[46:49], v27, s[26:27]
	s_mov_b64 exec, s[0:1]
	s_add_u32 s24, s24, 0xe0
	s_cmpk_ge_u32 s25, 9600
	s_cbranch_scc1 .Ltc2_exit
	s_waitcnt vmcnt(15)
	v_add_u32_e32 v28, 0, v22
	ds_write2_b32 v28, v50, v51 offset1:1
	ds_write2_b32 v28, v52, v53 offset0:2 offset1:3
	v_add_u32_e32 v28, 0x2080, v28
	ds_write2_b32 v28, v54, v55 offset1:1
	ds_write2_b32 v28, v56, v57 offset0:2 offset1:3
	s_mov_b32 s21, s25
	s_mov_b32 s0, s21
	s_cmpk_lt_u32 s0, 9600
	s_cbranch_scc0 .Ltc2_c240
	s_and_b32 s1, s0, 31
	s_lshl_b32 s1, s1, 6
	s_lshr_b32 s21, s0, 5
	s_lshl_b32 s21, s21, 17
	s_add_u32 s1, s1, s21
	s_lshl_b32 s1, s1, 1
	s_add_u32 s1, s1, 0x4001000
	s_add_u32 s30, s68, s1
	s_addc_u32 s31, s69, 0
	s_movk_i32 s20, 0x800
	s_branch .Ltc2_d239

; __device__ __forceinline__ unsigned cvt_pk_bf16(float lo, float hi) { unsigned r; asm("v_cvt_pk_bf16_f32 %0, %1, %2" : "=v"(r) : "v"(lo), "v"(hi)); return r; }
; __device__ __forceinline__ void tconv_tile(LAS float* tile, const float* src, int ld, int k0, int n0, int mode, bf16_t* dst, int K) {
;     ...
;     for (int it = 0; it < 2; ++it) { const int idx = tid + it * 512, kk = idx >> 4, n4 = (idx & 15) * 4, nn = n0 + n4; int oc = nn; bool valid = true;
;         if (mode == 1) { if (nn < 7680) oc = nn; else if (nn < 18944) oc = nn + 48; else if (nn < INW) oc = 7680 + (nn - 18944); else valid = false; }
;         f32x4 v = (f32x4){0.f, 0.f, 0.f, 0.f}; if (valid) v = *(const f32x4*)(src + (size_t)(k0 + kk) * ld + oc);
;         tile[kk * 65 + n4 + 0] = v[0]; tile[kk * 65 + n4 + 1] = v[1]; tile[kk * 65 + n4 + 2] = v[2]; tile[kk * 65 + n4 + 3] = v[3]; }
;     __syncthreads();
;     { const int n = tid >> 3, k8 = (tid & 7) * 8; float v[8];
; #pragma unroll
;         for (int e = 0; e < 8; ++e) v[e] = tile[(k8 + e) * 65 + n];
;         u32x4 w; w.x = cvt_pk_bf16(v[0], v[1]); w.y = cvt_pk_bf16(v[2], v[3]); w.z = cvt_pk_bf16(v[4], v[5]); w.w = cvt_pk_bf16(v[6], v[7]);
;         *(u32x4*)(dst + (size_t)(n0 + n) * K + k0 + k8) = w; }
;     __syncthreads();
.Ltc2_d246:
	v_mov_b32_e32 v50, 0
	v_mov_b32_e32 v51, 0
	v_mov_b32_e32 v52, 0
	v_mov_b32_e32 v53, 0
	v_mov_b32_e32 v54, 0
	v_mov_b32_e32 v55, 0
	v_mov_b32_e32 v56, 0
	v_mov_b32_e32 v57, 0
	v_mul_u32_u24_e32 v26, s28, v20
	v_add_lshl_u32 v26, v26, v21, 2
	s_lshl_b32 s0, s28, 7
	v_add_u32_e32 v27, s0, v26
	v_cmp_gt_i32_e32 vcc, s29, v21
	s_and_saveexec_b64 s[0:1], vcc
	global_load_dwordx4 v[50:53], v26, s[26:27]
	global_load_dwordx4 v[54:57], v27, s[26:27]
	s_mov_b64 exec, s[0:1]
	s_add_u32 s24, s24, 0xe0
	s_cmpk_ge_u32 s25, 9600
	s_cbranch_scc1 .Ltc2_exit
	s_waitcnt vmcnt(15)
	v_add_u32_e32 v28, 16896, v22
	ds_write2_b32 v28, v58, v59 offset1:1
	ds_write2_b32 v28, v60, v61 offset0:2 offset1:3
	v_add_u32_e32 v28, 0x2080, v28
	ds_write2_b32 v28, v62, v63 offset1:1
	ds_write2_b32 v28, v64, v65 offset0:2 offset1:3
	s_mov_b32 s21, s25
	s_mov_b32 s0, s21
	s_cmpk_lt_u32 s0, 9600
	s_cbranch_scc0 .Ltc2_c260
	s_and_b32 s1, s0, 31
	s_lshl_b32 s1, s1, 6
	s_lshr_b32 s21, s0, 5
	s_lshl_b32 s21, s21, 17
	s_add_u32 s1, s1, s21
	s_lshl_b32 s1, s1, 1
	s_add_u32 s1, s1, 0x4001000
	s_add_u32 s30, s68, s1
	s_addc_u32 s31, s69, 0
	s_movk_i32 s20, 0x800
	s_branch .Ltc2_d259

; __device__ __forceinline__ unsigned cvt_pk_bf16(float lo, float hi) { unsigned r; asm("v_cvt_pk_bf16_f32 %0, %1, %2" : "=v"(r) : "v"(lo), "v"(hi)); return r; }
; __device__ __forceinline__ void tconv_tile(LAS float* tile, const float* src, int ld, int k0, int n0, int mode, bf16_t* dst, int K) {
;     ...
;     for (int it = 0; it < 2; ++it) { const int idx = tid + it * 512, kk = idx >> 4, n4 = (idx & 15) * 4, nn = n0 + n4; int oc = nn; bool valid = true;
;         if (mode == 1) { if (nn < 7680) oc = nn; else if (nn < 18944) oc = nn + 48; else if (nn < INW) oc = 7680 + (nn - 18944); else valid = false; }
;         f32x4 v = (f32x4){0.f, 0.f, 0.f, 0.f}; if (valid) v = *(const f32x4*)(src + (size_t)(k0 + kk) * ld + oc);
;         tile[kk * 65 + n4 + 0] = v[0]; tile[kk * 65 + n4 + 1] = v[1]; tile[kk * 65 + n4 + 2] = v[2]; tile[kk * 65 + n4 + 3] = v[3]; }
;     __syncthreads();
;     { const int n = tid >> 3, k8 = (tid & 7) * 8; float v[8];
; #pragma unroll
;         for (int e = 0; e < 8; ++e) v[e] = tile[(k8 + e) * 65 + n];
;         u32x4 w; w.x = cvt_pk_bf16(v[0], v[1]); w.y = cvt_pk_bf16(v[2], v[3]); w.z = cvt_pk_bf16(v[4], v[5]); w.w = cvt_pk_bf16(v[6], v[7]);
;         *(u32x4*)(dst + (size_t)(n0 + n) * K + k0 + k8) = w; }
;     __syncthreads();
.Ltc2_d266:
	v_mov_b32_e32 v58, 0
	v_mov_b32_e32 v59, 0
	v_mov_b32_e32 v60, 0
	v_mov_b32_e32 v61, 0
	v_mov_b32_e32 v62, 0
	v_mov_b32_e32 v63, 0
	v_mov_b32_e32 v64, 0
	v_mov_b32_e32 v65, 0
	v_mul_u32_u24_e32 v26, s28, v20
	v_add_lshl_u32 v26, v26, v21, 2
	s_lshl_b32 s0, s28, 7
	v_add_u32_e32 v27, s0, v26
	v_cmp_gt_i32_e32 vcc, s29, v21
	s_and_saveexec_b64 s[0:1], vcc
	global_load_dwordx4 v[58:61], v26, s[26:27]
	global_load_dwordx4 v[62:65], v27, s[26:27]
	s_mov_b64 exec, s[0:1]
	s_add_u32 s24, s24, 0xe0
	s_cmpk_ge_u32 s25, 9600
	s_cbranch_scc1 .Ltc2_exit
	s_waitcnt vmcnt(15)
	v_add_u32_e32 v28, 0, v22
	ds_write2_b32 v28, v78, v79 offset1:1
	ds_write2_b32 v28, v80, v81 offset0:2 offset1:3
	v_add_u32_e32 v28, 0x2080, v28
	ds_write2_b32 v28, v82, v83 offset1:1
	ds_write2_b32 v28, v84, v85 offset0:2 offset1:3
	s_mov_b32 s21, s25
	s_mov_b32 s0, s21
	s_cmpk_lt_u32 s0, 9600
	s_cbranch_scc0 .Ltc2_c280
	s_and_b32 s1, s0, 31
	s_lshl_b32 s1, s1, 6
	s_lshr_b32 s21, s0, 5
	s_lshl_b32 s21, s21, 17
	s_add_u32 s1, s1, s21
	s_lshl_b32 s1, s1, 1
	s_add_u32 s1, s1, 0x4001000
	s_add_u32 s30, s68, s1
	s_addc_u32 s31, s69, 0
	s_movk_i32 s20, 0x800
	s_branch .Ltc2_d279

; __device__ __forceinline__ unsigned cvt_pk_bf16(float lo, float hi) { unsigned r; asm("v_cvt_pk_bf16_f32 %0, %1, %2" : "=v"(r) : "v"(lo), "v"(hi)); return r; }
; __device__ __forceinline__ void tconv_tile(LAS float* tile, const float* src, int ld, int k0, int n0, int mode, bf16_t* dst, int K) {
;     ...
;     for (int it = 0; it < 2; ++it) { const int idx = tid + it * 512, kk = idx >> 4, n4 = (idx & 15) * 4, nn = n0 + n4; int oc = nn; bool valid = true;
;         if (mode == 1) { if (nn < 7680) oc = nn; else if (nn < 18944) oc = nn + 48; else if (nn < INW) oc = 7680 + (nn - 18944); else valid = false; }
;         f32x4 v = (f32x4){0.f, 0.f, 0.f, 0.f}; if (valid) v = *(const f32x4*)(src + (size_t)(k0 + kk) * ld + oc);
;         tile[kk * 65 + n4 + 0] = v[0]; tile[kk * 65 + n4 + 1] = v[1]; tile[kk * 65 + n4 + 2] = v[2]; tile[kk * 65 + n4 + 3] = v[3]; }
;     __syncthreads();
;     { const int n = tid >> 3, k8 = (tid & 7) * 8; float v[8];
; #pragma unroll
;         for (int e = 0; e < 8; ++e) v[e] = tile[(k8 + e) * 65 + n];
;         u32x4 w; w.x = cvt_pk_bf16(v[0], v[1]); w.y = cvt_pk_bf16(v[2], v[3]); w.z = cvt_pk_bf16(v[4], v[5]); w.w = cvt_pk_bf16(v[6], v[7]);
;         *(u32x4*)(dst + (size_t)(n0 + n) * K + k0 + k8) = w; }
;     __syncthreads();
.Ltc2_d306:
	v_mov_b32_e32 v86, 0
	v_mov_b32_e32 v87, 0
	v_mov_b32_e32 v88, 0
	v_mov_b32_e32 v89, 0
	v_mov_b32_e32 v90, 0
	v_mov_b32_e32 v91, 0
	v_mov_b32_e32 v92, 0
	v_mov_b32_e32 v93, 0
	v_mul_u32_u24_e32 v26, s28, v20
	v_add_lshl_u32 v26, v26, v21, 2
	s_lshl_b32 s0, s28, 7
	v_add_u32_e32 v27, s0, v26
	v_cmp_gt_i32_e32 vcc, s29, v21
	s_and_saveexec_b64 s[0:1], vcc
	global_load_dwordx4 v[86:89], v26, s[26:27]
	global_load_dwordx4 v[90:93], v27, s[26:27]
	s_mov_b64 exec, s[0:1]
	s_add_u32 s24, s24, 0xe0
	s_branch .Ltc2_loop

; __device__ __forceinline__ void prologue(LAS unsigned char* lds, const Ctx& P, int l) {
;     ...
;     for (int t = blockIdx.x; t < T_ALL; t += G) {
;         int q = t;
;         if (q < T_IN) { const int kt = q & 31, ntl = q >> 5; tconv_tile(tile, P.in[3] + (size_t)l * DM * INW, INW, kt * 64, ntl * 64, 1, (bf16_t*)(ws + WS_WIN), DM); continue; }
; __global__ void __launch_bounds__(512, 2) fwd_megakernel(Params PK) {
;     ...
;         } else if (ph == 8) {
;             if (l == 0) prologue(lds, P, 1);
.LBB0_868:
	v_mov_b32_e32 v26, 0x23f00
	ds_read_b64 v[34:35], v26 offset:24
	ds_read_b64 v[36:37], v26 offset:184
	ds_read_b64 v[38:39], v26 offset:192
	ds_read_b64 v[40:41], v26 offset:176
	ds_read_b64 v[42:43], v26 offset:136
	ds_read_b64 v[44:45], v26 offset:144
	ds_read_b64 v[46:47], v26 offset:80
	ds_read_b64 v[48:49], v26 offset:96
	s_waitcnt lgkmcnt(0)
	v_readfirstlane_b32 s4, v34
	v_readfirstlane_b32 s5, v35
	v_readfirstlane_b32 s6, v36
	v_readfirstlane_b32 s7, v37
	v_readfirstlane_b32 s8, v38
	v_readfirstlane_b32 s9, v39
	v_readfirstlane_b32 s10, v40
	v_readfirstlane_b32 s11, v41
	v_readfirstlane_b32 s12, v42
	v_readfirstlane_b32 s13, v43
	v_readfirstlane_b32 s14, v44
	v_readfirstlane_b32 s15, v45
	v_readfirstlane_b32 s16, v46
	v_readfirstlane_b32 s17, v47
	v_readfirstlane_b32 s18, v48
	v_readfirstlane_b32 s19, v49
	s_nop 3
	s_add_u32 s4, s4, 0x9460000
	s_addc_u32 s5, s5, 0
	s_add_u32 s6, s6, 0x2000000
	s_addc_u32 s7, s7, 0
	s_add_u32 s8, s8, 0x1000000
	s_addc_u32 s9, s9, 0
	s_add_u32 s10, s10, 0x1000000
	s_addc_u32 s11, s11, 0
	s_add_u32 s12, s12, 0x200000
	s_addc_u32 s13, s13, 0
	s_add_u32 s14, s14, 0x200000
	s_addc_u32 s15, s15, 0
	s_add_u32 s16, s16, 0x80000
	s_addc_u32 s17, s17, 0
	s_add_u32 s18, s18, 0x80000
	s_addc_u32 s19, s19, 0
	v_lshrrev_b32_e32 v20, 4, v234
	v_and_b32_e32 v21, 15, v234
	v_lshlrev_b32_e32 v21, 2, v21
	v_mul_u32_u24_e32 v22, 0x104, v20
	v_lshl_add_u32 v22, v21, 2, v22
	v_lshrrev_b32_e32 v24, 3, v234
	v_and_b32_e32 v25, 7, v234
	v_lshlrev_b32_e32 v25, 3, v25
	v_mul_u32_u24_e32 v23, 0x104, v25
	v_lshl_add_u32 v23, v24, 2, v23
	s_add_u32 s24, s2, 9472
	s_add_u32 s0, s24, 0x100
	s_cmpk_lt_u32 s24, 9600
	s_cselect_b32 s24, s0, s24
	s_mov_b32 s25, s24
	s_min_u32 s0, s24, 14015
	s_mov_b32 s21, s0
	s_mov_b32 s0, s21
	s_cmpk_lt_u32 s0, 9600
	s_cbranch_scc0 .Ltc1_c2
	s_and_b32 s1, s0, 31
	s_lshl_b32 s1, s1, 6
	s_lshr_b32 s21, s0, 5
	s_lshl_b32 s21, s21, 6
	s_movk_i32 s29, 64
	s_cmpk_lt_u32 s21, 7680
	s_cbranch_scc1 .Ltc1_n4
	s_cmpk_lt_u32 s21, 18944
	s_cbranch_scc0 .Ltc1_t3
	s_add_u32 s21, s21, 48
	s_branch .Ltc1_n4

; __device__ __forceinline__ void prologue(LAS unsigned char* lds, const Ctx& P, int l) {
;     ...
;     for (int t = blockIdx.x; t < T_ALL; t += G) {
;         int q = t;
;         if (q < T_IN) { const int kt = q & 31, ntl = q >> 5; tconv_tile(tile, P.in[3] + (size_t)l * DM * INW, INW, kt * 64, ntl * 64, 1, (bf16_t*)(ws + WS_WIN), DM); continue; }
.LBB0_1011:
	v_mov_b32_e32 v26, 0x23f00
	ds_read_b64 v[34:35], v26 offset:24
	ds_read_b64 v[36:37], v26 offset:184
	ds_read_b64 v[38:39], v26 offset:192
	ds_read_b64 v[40:41], v26 offset:176
	ds_read_b64 v[42:43], v26 offset:136
	ds_read_b64 v[44:45], v26 offset:144
	ds_read_b64 v[46:47], v26 offset:80
	ds_read_b64 v[48:49], v26 offset:96
	s_waitcnt lgkmcnt(0)
	v_readfirstlane_b32 s4, v34
	v_readfirstlane_b32 s5, v35
	v_readfirstlane_b32 s6, v36
	v_readfirstlane_b32 s7, v37
	v_readfirstlane_b32 s8, v38
	v_readfirstlane_b32 s9, v39
	v_readfirstlane_b32 s10, v40
	v_readfirstlane_b32 s11, v41
	v_readfirstlane_b32 s12, v42
	v_readfirstlane_b32 s13, v43
	v_readfirstlane_b32 s14, v44
	v_readfirstlane_b32 s15, v45
	v_readfirstlane_b32 s16, v46
	v_readfirstlane_b32 s17, v47
	v_readfirstlane_b32 s18, v48
	v_readfirstlane_b32 s19, v49
	v_lshrrev_b32_e32 v20, 4, v234
	v_and_b32_e32 v21, 15, v234
	v_lshlrev_b32_e32 v21, 2, v21
	v_mul_u32_u24_e32 v22, 0x104, v20
	v_lshl_add_u32 v22, v21, 2, v22
	v_lshrrev_b32_e32 v24, 3, v234
	v_and_b32_e32 v25, 7, v234
	v_lshlrev_b32_e32 v25, 3, v25
	v_mul_u32_u24_e32 v23, 0x104, v25
	v_lshl_add_u32 v23, v24, 2, v23
	s_mov_b32 s24, s2
	s_mov_b32 s25, s24
	s_min_u32 s0, s24, 14015
	s_mov_b32 s21, s0
	s_mov_b32 s0, s21
	s_cmpk_lt_u32 s0, 9600
	s_cbranch_scc0 .Ltc0_c2
	s_and_b32 s1, s0, 31
	s_lshl_b32 s1, s1, 6
	s_lshr_b32 s21, s0, 5
	s_lshl_b32 s21, s21, 6
	s_movk_i32 s29, 64
	s_cmpk_lt_u32 s21, 7680
	s_cbranch_scc1 .Ltc0_n4
	s_cmpk_lt_u32 s21, 18944
	s_cbranch_scc0 .Ltc0_t3
	s_add_u32 s21, s21, 48
	s_branch .Ltc0_n4
